# grid barriers: non-leader L1 invalidate issued before polling the release word; state-scan stores write-through, no L2 writeback at the split arrive; rms loop as v20
# speedup vs baseline: 1.0209x; 1.0209x over previous
; __device__ __forceinline__ unsigned xb_ld(unsigned* p)              { return __hip_atomic_load(p, __ATOMIC_RELAXED, __HIP_MEMORY_SCOPE_AGENT); }
; __device__ __forceinline__ unsigned xb_add(unsigned* p, unsigned v) { return __hip_atomic_fetch_add(p, v, __ATOMIC_RELAXED, __HIP_MEMORY_SCOPE_AGENT); }
; #define XB_SPIN(cond, bar) do { unsigned _sp = 0; while (cond) { __builtin_amdgcn_s_sleep(1); \
;     if ((++_sp & 255u) == 0u) { if (xb_ld(&(bar)[XB_TMO])) break; if (_sp > XB_SPIN_CAP) { atomicAdd(&(bar)[XB_TMO], 1u); break; } } } } while (0)
; __device__ __forceinline__ void xcd_barrier(const XcdBarrier& b) {
;     ...
;         const unsigned old = xb_add(&bar[XB_XSUB(b.x)], 1u);
;         const unsigned gen = old / nloc;
;         if (old + 1u == (gen + 1u) * nloc) {
;             __builtin_amdgcn_fence(__ATOMIC_RELEASE, "agent");
;             asm volatile("s_waitcnt vmcnt(0)" ::: "memory");
;             const unsigned og = xb_add(&bar[XB_TOP], 1u);
;             const unsigned tg = og / nx;
;             if (og + 1u == (tg + 1u) * nx) xb_add(&bar[XB_TOPGEN], 1u);
;             else XB_SPIN(xb_ld(&bar[XB_TOPGEN]) == tg, bar);
;             __builtin_amdgcn_fence(__ATOMIC_ACQUIRE, "agent");
;             xb_add(&bar[XB_XGEN(b.x)], 1u);
;             asm volatile("s_waitcnt vmcnt(0)" ::: "memory");
;         } else {
;             XB_SPIN(xb_ld(&bar[XB_XGEN(b.x)]) == gen, bar);
;             __builtin_amdgcn_fence(__ATOMIC_ACQUIRE, "agent");
;             asm volatile("s_waitcnt vmcnt(0)" ::: "memory");
.LBB0_126:
	s_or_b64 exec, exec, s[16:17]
	v_cvt_f32_u32_e32 v4, v2
	s_waitcnt vmcnt(0)
	v_readfirstlane_b32 s3, v3
	v_sub_u32_e32 v3, 0, v2
	v_rcp_iflag_f32_e32 v4, v4
	v_add_u32_e32 v5, s3, v1
	v_mul_f32_e32 v4, 0x4f7ffffe, v4
	v_cvt_u32_f32_e32 v4, v4
	v_mul_lo_u32 v1, v3, v4
	v_mul_hi_u32 v1, v4, v1
	v_add_u32_e32 v1, v4, v1
	v_mul_hi_u32 v1, v5, v1
	v_mul_lo_u32 v3, v1, v2
	v_sub_u32_e32 v3, v5, v3
	v_add_u32_e32 v4, 1, v1
	v_cmp_ge_u32_e32 vcc, v3, v2
	s_nop 1
	v_cndmask_b32_e32 v1, v1, v4, vcc
	v_sub_u32_e32 v4, v3, v2
	v_cndmask_b32_e32 v3, v3, v4, vcc
	v_add_u32_e32 v4, 1, v1
	v_cmp_ge_u32_e32 vcc, v3, v2
	v_add_u32_e32 v3, 1, v5
	s_nop 0
	v_cndmask_b32_e32 v1, v1, v4, vcc
	v_mul_lo_u32 v4, v2, v1
	v_add_u32_e32 v2, v4, v2
	v_cmp_ne_u32_e32 vcc, v3, v2
	s_and_saveexec_b64 s[16:17], vcc
	s_xor_b64 s[16:17], exec, s[16:17]
	s_cbranch_execz .LBB0_140
	v_readlane_b32 s4, v240, 14
	s_waitcnt lgkmcnt(0)
	v_mov_b32_e32 v0, 0
	v_readlane_b32 s5, v240, 15
	s_nop 4
	buffer_inv sc1
	global_load_dword v2, v0, s[4:5] sc1
	s_waitcnt vmcnt(0)
	v_cmp_eq_u32_e32 vcc, v2, v1
	s_and_saveexec_b64 s[18:19], vcc
	s_cbranch_execz .LBB0_139
	s_mov_b32 s3, 1
	s_mov_b64 s[20:21], 0
	s_branch .LBB0_130

; __device__ __forceinline__ unsigned xb_ld(unsigned* p)              { return __hip_atomic_load(p, __ATOMIC_RELAXED, __HIP_MEMORY_SCOPE_AGENT); }
; #define XB_SPIN(cond, bar) do { unsigned _sp = 0; while (cond) { __builtin_amdgcn_s_sleep(1); \
;     if ((++_sp & 255u) == 0u) { if (xb_ld(&(bar)[XB_TMO])) break; if (_sp > XB_SPIN_CAP) { atomicAdd(&(bar)[XB_TMO], 1u); break; } } } } while (0)
; __device__ __forceinline__ void xcd_barrier(const XcdBarrier& b) {
;     ...
;             XB_SPIN(xb_ld(&bar[XB_XGEN(b.x)]) == gen, bar);
;             __builtin_amdgcn_fence(__ATOMIC_ACQUIRE, "agent");
;             asm volatile("s_waitcnt vmcnt(0)" ::: "memory");
.LBB0_139:
	s_or_b64 exec, exec, s[18:19]
	s_waitcnt vmcnt(0)
	s_waitcnt vmcnt(0)

; __device__ __forceinline__ unsigned xb_ld(unsigned* p)              { return __hip_atomic_load(p, __ATOMIC_RELAXED, __HIP_MEMORY_SCOPE_AGENT); }
; __device__ __forceinline__ unsigned xb_add(unsigned* p, unsigned v) { return __hip_atomic_fetch_add(p, v, __ATOMIC_RELAXED, __HIP_MEMORY_SCOPE_AGENT); }
; #define XB_SPIN(cond, bar) do { unsigned _sp = 0; while (cond) { __builtin_amdgcn_s_sleep(1); \
;     if ((++_sp & 255u) == 0u) { if (xb_ld(&(bar)[XB_TMO])) break; if (_sp > XB_SPIN_CAP) { atomicAdd(&(bar)[XB_TMO], 1u); break; } } } } while (0)
; __device__ __forceinline__ void xcd_barrier(const XcdBarrier& b) {
;     ...
;         const unsigned old = xb_add(&bar[XB_XSUB(b.x)], 1u);
;         const unsigned gen = old / nloc;
;         if (old + 1u == (gen + 1u) * nloc) {
;             __builtin_amdgcn_fence(__ATOMIC_RELEASE, "agent");
;             asm volatile("s_waitcnt vmcnt(0)" ::: "memory");
;             const unsigned og = xb_add(&bar[XB_TOP], 1u);
;             const unsigned tg = og / nx;
;             if (og + 1u == (tg + 1u) * nx) xb_add(&bar[XB_TOPGEN], 1u);
;             else XB_SPIN(xb_ld(&bar[XB_TOPGEN]) == tg, bar);
;             __builtin_amdgcn_fence(__ATOMIC_ACQUIRE, "agent");
;             xb_add(&bar[XB_XGEN(b.x)], 1u);
;             asm volatile("s_waitcnt vmcnt(0)" ::: "memory");
;         } else {
;             XB_SPIN(xb_ld(&bar[XB_XGEN(b.x)]) == gen, bar);
.LBB0_223:
	s_or_b64 exec, exec, s[18:19]
	v_cvt_f32_u32_e32 v4, v2
	s_waitcnt vmcnt(0)
	v_readfirstlane_b32 s3, v3
	v_sub_u32_e32 v3, 0, v2
	v_rcp_iflag_f32_e32 v4, v4
	v_add_u32_e32 v5, s3, v1
	v_mul_f32_e32 v4, 0x4f7ffffe, v4
	v_cvt_u32_f32_e32 v4, v4
	v_mul_lo_u32 v1, v3, v4
	v_mul_hi_u32 v1, v4, v1
	v_add_u32_e32 v1, v4, v1
	v_mul_hi_u32 v1, v5, v1
	v_mul_lo_u32 v3, v1, v2
	v_sub_u32_e32 v3, v5, v3
	v_add_u32_e32 v4, 1, v1
	v_cmp_ge_u32_e32 vcc, v3, v2
	s_nop 1
	v_cndmask_b32_e32 v1, v1, v4, vcc
	v_sub_u32_e32 v4, v3, v2
	v_cndmask_b32_e32 v3, v3, v4, vcc
	v_add_u32_e32 v4, 1, v1
	v_cmp_ge_u32_e32 vcc, v3, v2
	v_add_u32_e32 v3, 1, v5
	s_nop 0
	v_cndmask_b32_e32 v1, v1, v4, vcc
	v_mul_lo_u32 v4, v2, v1
	v_add_u32_e32 v2, v4, v2
	v_cmp_ne_u32_e32 vcc, v3, v2
	s_and_saveexec_b64 s[18:19], vcc
	s_xor_b64 s[18:19], exec, s[18:19]
	s_cbranch_execz .LBB0_237
	v_readlane_b32 s0, v240, 14
	s_waitcnt lgkmcnt(0)
	v_mov_b32_e32 v0, 0
	v_readlane_b32 s1, v240, 15
	s_nop 4
	buffer_inv sc1
	global_load_dword v2, v0, s[0:1] sc1
	s_waitcnt vmcnt(0)
	v_cmp_eq_u32_e32 vcc, v2, v1
	s_and_saveexec_b64 s[22:23], vcc
	s_cbranch_execz .LBB0_236
	s_mov_b32 s3, 1
	s_mov_b64 s[24:25], 0
	s_branch .LBB0_227

; __device__ __forceinline__ unsigned xb_ld(unsigned* p)              { return __hip_atomic_load(p, __ATOMIC_RELAXED, __HIP_MEMORY_SCOPE_AGENT); }
; #define XB_SPIN(cond, bar) do { unsigned _sp = 0; while (cond) { __builtin_amdgcn_s_sleep(1); \
;     if ((++_sp & 255u) == 0u) { if (xb_ld(&(bar)[XB_TMO])) break; if (_sp > XB_SPIN_CAP) { atomicAdd(&(bar)[XB_TMO], 1u); break; } } } } while (0)
; __device__ __forceinline__ void xcd_barrier(const XcdBarrier& b) {
;     ...
;             XB_SPIN(xb_ld(&bar[XB_XGEN(b.x)]) == gen, bar);
;             __builtin_amdgcn_fence(__ATOMIC_ACQUIRE, "agent");
;             asm volatile("s_waitcnt vmcnt(0)" ::: "memory");
.LBB0_236:
	s_or_b64 exec, exec, s[22:23]
	s_waitcnt vmcnt(0)
	s_waitcnt vmcnt(0)

; __device__ __forceinline__ unsigned xb_ld(unsigned* p)              { return __hip_atomic_load(p, __ATOMIC_RELAXED, __HIP_MEMORY_SCOPE_AGENT); }
; __device__ __forceinline__ unsigned xb_add(unsigned* p, unsigned v) { return __hip_atomic_fetch_add(p, v, __ATOMIC_RELAXED, __HIP_MEMORY_SCOPE_AGENT); }
; #define XB_SPIN(cond, bar) do { unsigned _sp = 0; while (cond) { __builtin_amdgcn_s_sleep(1); \
;     if ((++_sp & 255u) == 0u) { if (xb_ld(&(bar)[XB_TMO])) break; if (_sp > XB_SPIN_CAP) { atomicAdd(&(bar)[XB_TMO], 1u); break; } } } } while (0)
; __device__ __forceinline__ void xcd_barrier(const XcdBarrier& b) {
;     ...
;         const unsigned old = xb_add(&bar[XB_XSUB(b.x)], 1u);
;         const unsigned gen = old / nloc;
;         if (old + 1u == (gen + 1u) * nloc) {
;             __builtin_amdgcn_fence(__ATOMIC_RELEASE, "agent");
;             asm volatile("s_waitcnt vmcnt(0)" ::: "memory");
;             const unsigned og = xb_add(&bar[XB_TOP], 1u);
;             const unsigned tg = og / nx;
;             if (og + 1u == (tg + 1u) * nx) xb_add(&bar[XB_TOPGEN], 1u);
;             else XB_SPIN(xb_ld(&bar[XB_TOPGEN]) == tg, bar);
;             __builtin_amdgcn_fence(__ATOMIC_ACQUIRE, "agent");
;             xb_add(&bar[XB_XGEN(b.x)], 1u);
;             asm volatile("s_waitcnt vmcnt(0)" ::: "memory");
;         } else {
;             XB_SPIN(xb_ld(&bar[XB_XGEN(b.x)]) == gen, bar);
.LBB0_416:
	s_or_b64 exec, exec, s[24:25]
	v_cvt_f32_u32_e32 v4, v2
	s_waitcnt vmcnt(0)
	v_readfirstlane_b32 s24, v3
	v_sub_u32_e32 v3, 0, v2
	v_rcp_iflag_f32_e32 v4, v4
	v_add_u32_e32 v5, s24, v1
	v_mul_f32_e32 v4, 0x4f7ffffe, v4
	v_cvt_u32_f32_e32 v4, v4
	v_mul_lo_u32 v1, v3, v4
	v_mul_hi_u32 v1, v4, v1
	v_add_u32_e32 v1, v4, v1
	v_mul_hi_u32 v1, v5, v1
	v_mul_lo_u32 v3, v1, v2
	v_sub_u32_e32 v3, v5, v3
	v_add_u32_e32 v4, 1, v1
	v_cmp_ge_u32_e32 vcc, v3, v2
	s_nop 1
	v_cndmask_b32_e32 v1, v1, v4, vcc
	v_sub_u32_e32 v4, v3, v2
	v_cndmask_b32_e32 v3, v3, v4, vcc
	v_add_u32_e32 v4, 1, v1
	v_cmp_ge_u32_e32 vcc, v3, v2
	v_add_u32_e32 v3, 1, v5
	s_nop 0
	v_cndmask_b32_e32 v1, v1, v4, vcc
	v_mul_lo_u32 v4, v2, v1
	v_add_u32_e32 v2, v4, v2
	v_cmp_ne_u32_e32 vcc, v3, v2
	s_and_saveexec_b64 s[24:25], vcc
	s_xor_b64 s[24:25], exec, s[24:25]
	s_cbranch_execz .LBB0_430
	v_readlane_b32 s0, v240, 14
	s_waitcnt lgkmcnt(0)
	v_mov_b32_e32 v0, 0
	v_readlane_b32 s1, v240, 15
	s_nop 4
	buffer_inv sc1
	global_load_dword v2, v0, s[0:1] sc1
	s_waitcnt vmcnt(0)
	v_cmp_eq_u32_e32 vcc, v2, v1
	s_and_saveexec_b64 s[38:39], vcc
	s_cbranch_execz .LBB0_429
	s_mov_b32 s26, 1
	s_mov_b64 s[42:43], 0
	s_branch .LBB0_420

; __device__ __forceinline__ unsigned xb_ld(unsigned* p)              { return __hip_atomic_load(p, __ATOMIC_RELAXED, __HIP_MEMORY_SCOPE_AGENT); }
; #define XB_SPIN(cond, bar) do { unsigned _sp = 0; while (cond) { __builtin_amdgcn_s_sleep(1); \
;     if ((++_sp & 255u) == 0u) { if (xb_ld(&(bar)[XB_TMO])) break; if (_sp > XB_SPIN_CAP) { atomicAdd(&(bar)[XB_TMO], 1u); break; } } } } while (0)
; __device__ __forceinline__ void xcd_barrier(const XcdBarrier& b) {
;     ...
;             XB_SPIN(xb_ld(&bar[XB_XGEN(b.x)]) == gen, bar);
;             __builtin_amdgcn_fence(__ATOMIC_ACQUIRE, "agent");
;             asm volatile("s_waitcnt vmcnt(0)" ::: "memory");
.LBB0_429:
	s_or_b64 exec, exec, s[38:39]
	s_waitcnt vmcnt(0)
	s_waitcnt vmcnt(0)

; __device__ __forceinline__ unsigned xb_ld(unsigned* p)              { return __hip_atomic_load(p, __ATOMIC_RELAXED, __HIP_MEMORY_SCOPE_AGENT); }
; __device__ __forceinline__ unsigned xb_add(unsigned* p, unsigned v) { return __hip_atomic_fetch_add(p, v, __ATOMIC_RELAXED, __HIP_MEMORY_SCOPE_AGENT); }
; #define XB_SPIN(cond, bar) do { unsigned _sp = 0; while (cond) { __builtin_amdgcn_s_sleep(1); \
;     if ((++_sp & 255u) == 0u) { if (xb_ld(&(bar)[XB_TMO])) break; if (_sp > XB_SPIN_CAP) { atomicAdd(&(bar)[XB_TMO], 1u); break; } } } } while (0)
; __device__ __forceinline__ void xcd_barrier(const XcdBarrier& b) {
;     ...
;         const unsigned old = xb_add(&bar[XB_XSUB(b.x)], 1u);
;         const unsigned gen = old / nloc;
;         if (old + 1u == (gen + 1u) * nloc) {
;             __builtin_amdgcn_fence(__ATOMIC_RELEASE, "agent");
;             asm volatile("s_waitcnt vmcnt(0)" ::: "memory");
;             const unsigned og = xb_add(&bar[XB_TOP], 1u);
;             const unsigned tg = og / nx;
;             if (og + 1u == (tg + 1u) * nx) xb_add(&bar[XB_TOPGEN], 1u);
;             else XB_SPIN(xb_ld(&bar[XB_TOPGEN]) == tg, bar);
;             __builtin_amdgcn_fence(__ATOMIC_ACQUIRE, "agent");
;             xb_add(&bar[XB_XGEN(b.x)], 1u);
;             asm volatile("s_waitcnt vmcnt(0)" ::: "memory");
;         } else {
;             XB_SPIN(xb_ld(&bar[XB_XGEN(b.x)]) == gen, bar);
.LBB0_477:
	s_or_b64 exec, exec, s[20:21]
	v_cvt_f32_u32_e32 v4, v2
	s_waitcnt vmcnt(0)
	v_readfirstlane_b32 s20, v3
	v_sub_u32_e32 v3, 0, v2
	v_rcp_iflag_f32_e32 v4, v4
	v_add_u32_e32 v5, s20, v1
	v_mul_f32_e32 v4, 0x4f7ffffe, v4
	v_cvt_u32_f32_e32 v4, v4
	v_mul_lo_u32 v1, v3, v4
	v_mul_hi_u32 v1, v4, v1
	v_add_u32_e32 v1, v4, v1
	v_mul_hi_u32 v1, v5, v1
	v_mul_lo_u32 v3, v1, v2
	v_sub_u32_e32 v3, v5, v3
	v_add_u32_e32 v4, 1, v1
	v_cmp_ge_u32_e32 vcc, v3, v2
	s_nop 1
	v_cndmask_b32_e32 v1, v1, v4, vcc
	v_sub_u32_e32 v4, v3, v2
	v_cndmask_b32_e32 v3, v3, v4, vcc
	v_add_u32_e32 v4, 1, v1
	v_cmp_ge_u32_e32 vcc, v3, v2
	v_add_u32_e32 v3, 1, v5
	s_nop 0
	v_cndmask_b32_e32 v1, v1, v4, vcc
	v_mul_lo_u32 v4, v2, v1
	v_add_u32_e32 v2, v4, v2
	v_cmp_ne_u32_e32 vcc, v3, v2
	s_and_saveexec_b64 s[20:21], vcc
	s_xor_b64 s[20:21], exec, s[20:21]
	s_cbranch_execz .LBB0_491
	v_readlane_b32 s0, v240, 14
	s_waitcnt lgkmcnt(0)
	v_mov_b32_e32 v0, 0
	v_readlane_b32 s1, v240, 15
	s_nop 4
	buffer_inv sc1
	global_load_dword v2, v0, s[0:1] sc1
	s_waitcnt vmcnt(0)
	v_cmp_eq_u32_e32 vcc, v2, v1
	s_and_saveexec_b64 s[22:23], vcc
	s_cbranch_execz .LBB0_490
	s_mov_b32 s26, 1
	s_mov_b64 s[24:25], 0
	s_branch .LBB0_481

; __device__ __forceinline__ unsigned pk2(float lo, float hi) { f32x2 v = {lo, hi}; bf16x2_t b = __builtin_convertvector(v, bf16x2_t); return __builtin_bit_cast(unsigned, b); }
; __device__ __forceinline__ float ex2(float x) { return __builtin_amdgcn_exp2f(x); }
; __device__ __forceinline__ void ssd_state_scan(const Args& a) {
;     ...
;     for (int e = blockIdx.x * NTHREADS + tid; e < NB * 8 * 2 * 1024; e += gridDim.x * NTHREADS) {
;         const int seq = e >> 10, off = (e & 1023) * 8, dir = seq & 1, bh = seq >> 1;
;         const float* vb = vec + (size_t)bh * S_;
;         const size_t base = (size_t)seq * 8 * 8192 + off;
;         u32x4 sv[8]; float dec[8];
; #pragma unroll
;         for (int i = 0; i < 8; ++i) { const int qb = dir ? 7 - i : i; sv[i] = *(const u32x4*)(Sst + base + (size_t)qb * 8192);
;             const int L0 = qb * 256, L1 = L0 + 255;
;             if (dir == 0) dec[i] = ex2(vb[L1] - (qb ? vb[L0 - 1] : 0.f)); else dec[i] = ex2(vb[VS + L0] - (qb < 7 ? vb[VS + L1 + 1] : 0.f)); }
;         float h[8];
; #pragma unroll
;         for (int k = 0; k < 8; ++k) h[k] = 0.f;
; #pragma unroll
;         for (int i = 0; i < 8; ++i) { const int qb = dir ? 7 - i : i;
;             u32x4 o; o.x = pk2(h[0], h[1]); o.y = pk2(h[2], h[3]); o.z = pk2(h[4], h[5]); o.w = pk2(h[6], h[7]);
;             *(u32x4*)(Hst + base + (size_t)qb * 8192) = o;
;             const u32x4 v = sv[i]; const float d = dec[i];
;             h[0] = h[0] * d + bflo(v.x); h[1] = h[1] * d + bfhi(v.x); h[2] = h[2] * d + bflo(v.y); h[3] = h[3] * d + bfhi(v.y);
;             h[4] = h[4] * d + bflo(v.z); h[5] = h[5] * d + bfhi(v.z); h[6] = h[6] * d + bflo(v.w); h[7] = h[7] * d + bfhi(v.w); }
;     }
.LBB0_556:
	v_ashrrev_i32_e32 v2, 11, v33
	v_ashrrev_i32_e32 v3, 31, v2
	v_lshlrev_b64 v[2:3], 13, v[2:3]
	v_lshl_add_u64 v[18:19], s[18:19], 0, v[2:3]
	v_and_b32_e32 v2, 0x400, v33
	v_cmp_eq_u32_e32 vcc, 0, v2
	v_mov_b32_e32 v39, v17
	v_mov_b32_e32 v59, v17
	v_cndmask_b32_e64 v38, 4, 3, vcc
	v_cndmask_b32_e64 v58, 2, 5, vcc
	v_lshlrev_b32_e32 v34, 14, v38
	v_lshlrev_b32_e32 v38, 10, v38
	v_lshlrev_b32_e32 v64, 14, v58
	v_lshlrev_b32_e32 v58, 10, v58
	v_cndmask_b32_e32 v22, v41, v42, vcc
	v_mov_b32_e32 v23, v17
	v_cndmask_b32_e64 v31, 0, -1, vcc
	v_cndmask_b32_e64 v30, v43, -4, vcc
	v_lshl_add_u64 v[38:39], v[18:19], 0, v[38:39]
	v_lshl_add_u64 v[58:59], v[18:19], 0, v[58:59]
	v_lshl_add_u64 v[50:51], v[38:39], 0, v[22:23]
	v_lshl_add_u64 v[38:39], v[38:39], 0, v[30:31]
	v_lshl_add_u64 v[60:61], v[58:59], 0, v[22:23]
	v_lshl_add_u64 v[58:59], v[58:59], 0, v[30:31]
	global_load_dword v40, v[50:51], off
	v_ashrrev_i32_e32 v0, 10, v33
	global_load_dword v58, v[58:59], off
	v_ashrrev_i32_e32 v1, 31, v0
	global_load_dword v38, v[38:39], off
	v_and_b32_e32 v4, 0x1ff8, v37
	v_bfe_i32 v3, v33, 10, 1
	v_lshlrev_b64 v[20:21], 17, v[0:1]
	v_lshl_or_b32 v20, v4, 1, v20
	v_and_b32_e32 v4, 7, v3
	v_lshlrev_b32_e32 v16, 14, v4
	v_lshlrev_b32_e32 v4, 10, v4
	v_mov_b32_e32 v5, v17
	v_lshl_add_u64 v[4:5], v[18:19], 0, v[4:5]
	v_lshl_add_u64 v[4:5], v[4:5], 0, v[22:23]
	global_load_dword v4, v[4:5], off
	v_cndmask_b32_e64 v8, 6, 1, vcc
	v_cndmask_b32_e64 v12, 5, 2, vcc
	v_cndmask_b32_e64 v54, 3, 4, vcc
	v_cndmask_b32_e64 v63, 1, 6, vcc
	v_lshlrev_b32_e32 v26, 14, v8
	v_lshlrev_b32_e32 v8, 10, v8
	v_mov_b32_e32 v9, v17
	v_lshlrev_b32_e32 v28, 14, v12
	v_lshlrev_b32_e32 v12, 10, v12
	v_mov_b32_e32 v13, v17
	v_mov_b32_e32 v55, v17
	v_lshlrev_b32_e32 v70, 10, v63
	v_mov_b32_e32 v71, v17
	v_lshl_add_u64 v[8:9], v[18:19], 0, v[8:9]
	v_lshl_add_u64 v[12:13], v[18:19], 0, v[12:13]
	v_lshl_add_u64 v[10:11], v[8:9], 0, v[22:23]
	v_lshl_add_u64 v[8:9], v[8:9], 0, v[30:31]
	v_lshl_add_u64 v[14:15], v[12:13], 0, v[22:23]
	v_lshl_add_u64 v[12:13], v[12:13], 0, v[30:31]
	global_load_dword v10, v[10:11], off
	v_lshl_add_u64 v[24:25], s[78:79], 0, v[20:21]
	global_load_dword v14, v[14:15], off
	v_lshl_add_u64 v[0:1], v[24:25], 0, v[16:17]
	global_load_dwordx4 v[0:3], v[0:1], off
	v_mov_b32_e32 v27, v17
	v_mov_b32_e32 v29, v17
	v_mov_b32_e32 v35, v17
	v_mov_b32_e32 v39, v17
	v_mov_b32_e32 v65, v17
	v_lshlrev_b32_e32 v68, 14, v63
	v_mov_b32_e32 v69, v17
	v_lshl_add_u64 v[20:21], s[42:43], 0, v[20:21]
	global_load_dword v60, v[60:61], off
	s_waitcnt vmcnt(5)
	v_sub_f32_e32 v38, v40, v38
	v_exp_f32_e32 v40, v38
	v_lshlrev_b32_e32 v38, 14, v54
	v_lshlrev_b32_e32 v54, 10, v54
	v_lshl_add_u64 v[54:55], v[18:19], 0, v[54:55]
	v_lshl_add_u64 v[18:19], v[18:19], 0, v[70:71]
	v_lshl_add_u64 v[56:57], v[54:55], 0, v[22:23]
	v_lshl_add_u64 v[22:23], v[18:19], 0, v[22:23]
	v_lshl_add_u64 v[18:19], v[18:19], 0, v[30:31]
	global_load_dword v22, v[22:23], off
	v_lshl_add_u64 v[54:55], v[54:55], 0, v[30:31]
	global_load_dword v18, v[18:19], off
	v_lshl_add_u64 v[50:51], v[24:25], 0, v[38:39]
	global_load_dword v12, v[12:13], off
	s_waitcnt vmcnt(3)
	v_sub_f32_e32 v58, v60, v58
	global_load_dword v8, v[8:9], off
	v_exp_f32_e32 v45, v4
	global_load_dword v56, v[56:57], off
	v_lshl_add_u64 v[4:5], v[24:25], 0, v[26:27]
	global_load_dword v54, v[54:55], off
	v_lshl_add_u64 v[26:27], v[20:21], 0, v[26:27]
	global_load_dwordx4 v[4:7], v[4:5], off
	v_exp_f32_e32 v66, v58
	global_load_dwordx4 v[50:53], v[50:51], off
	s_waitcnt vmcnt(6)
	v_sub_f32_e32 v18, v22, v18
	v_lshl_add_u64 v[22:23], v[20:21], 0, v[16:17]
	s_waitcnt vmcnt(5)
	v_sub_f32_e32 v12, v14, v12
	v_exp_f32_e32 v36, v12
	v_lshl_add_u64 v[12:13], v[24:25], 0, v[34:35]
	global_load_dwordx4 v[12:15], v[12:13], off
	v_mul_f32_e32 v16, 0, v45
	global_store_dwordx4 v[22:23], v[46:49], off sc0 sc1
	v_lshlrev_b32_e32 v22, 16, v0
	v_and_b32_e32 v23, 0xffff0000, v0
	v_lshlrev_b32_e32 v0, 16, v1
	v_and_b32_e32 v1, 0xffff0000, v1
	v_pk_add_f32 v[30:31], v[16:17], v[0:1] op_sel_hi:[0,1]
	v_lshlrev_b32_e32 v0, 16, v2
	v_and_b32_e32 v1, 0xffff0000, v2
	v_pk_add_f32 v[70:71], v[16:17], v[0:1] op_sel_hi:[0,1]
	v_lshlrev_b32_e32 v0, 16, v3
	v_and_b32_e32 v1, 0xffff0000, v3
	v_pk_add_f32 v[22:23], v[16:17], v[22:23] op_sel_hi:[0,1]
	v_pk_add_f32 v[72:73], v[16:17], v[0:1] op_sel_hi:[0,1]
	v_cvt_pk_bf16_f32 v0, v22, v23
	v_cvt_pk_bf16_f32 v1, v30, v31
	v_cvt_pk_bf16_f32 v2, v70, v71
	v_cvt_pk_bf16_f32 v3, v72, v73
	global_store_dwordx4 v[26:27], v[0:3], off sc0 sc1
	v_exp_f32_e32 v18, v18
	s_waitcnt vmcnt(7)
	v_sub_f32_e32 v8, v10, v8
	v_exp_f32_e32 v32, v8
	v_lshl_add_u64 v[8:9], v[24:25], 0, v[28:29]
	global_load_dwordx4 v[8:11], v[8:9], off
	s_waitcnt vmcnt(6)
	v_sub_f32_e32 v54, v56, v54
	v_exp_f32_e32 v62, v54
	v_lshl_add_u64 v[54:55], v[24:25], 0, v[64:65]
	global_load_dwordx4 v[54:57], v[54:55], off
	v_lshl_add_u64 v[24:25], v[24:25], 0, v[68:69]
	global_load_dwordx4 v[58:61], v[24:25], off
	s_waitcnt vmcnt(7)
; __device__ __forceinline__ unsigned pk2(float lo, float hi) { f32x2 v = {lo, hi}; bf16x2_t b = __builtin_convertvector(v, bf16x2_t); return __builtin_bit_cast(unsigned, b); }
; __device__ __forceinline__ void ssd_state_scan(const Args& a) {
;     ...
;         for (int i = 0; i < 8; ++i) { const int qb = dir ? 7 - i : i;
;             u32x4 o; o.x = pk2(h[0], h[1]); o.y = pk2(h[2], h[3]); o.z = pk2(h[4], h[5]); o.w = pk2(h[6], h[7]);
;             *(u32x4*)(Hst + base + (size_t)qb * 8192) = o;
;             const u32x4 v = sv[i]; const float d = dec[i];
;             h[0] = h[0] * d + bflo(v.x); h[1] = h[1] * d + bfhi(v.x); h[2] = h[2] * d + bflo(v.y); h[3] = h[3] * d + bfhi(v.y);
;             h[4] = h[4] * d + bflo(v.z); h[5] = h[5] * d + bfhi(v.z); h[6] = h[6] * d + bflo(v.w); h[7] = h[7] * d + bfhi(v.w); }
;     }
; __device__ __forceinline__ void split_arrive(unsigned* cnt) {
;     asm volatile("s_waitcnt vmcnt(0)" ::: "memory");
;     __syncthreads();
;     if (threadIdx.x == 0) { __builtin_amdgcn_fence(__ATOMIC_RELEASE, "agent"); asm volatile("s_waitcnt vmcnt(0)" ::: "memory"); (void)__hip_atomic_fetch_add(cnt, 1u, __ATOMIC_RELAXED, __HIP_MEMORY_SCOPE_AGENT); }
	v_lshlrev_b32_e32 v0, 16, v4
	v_and_b32_e32 v1, 0xffff0000, v4
	v_pk_fma_f32 v[22:23], v[22:23], v[32:33], v[0:1] op_sel_hi:[1,0,1]
	v_lshlrev_b32_e32 v0, 16, v5
	v_and_b32_e32 v1, 0xffff0000, v5
	v_pk_fma_f32 v[4:5], v[30:31], v[32:33], v[0:1] op_sel_hi:[1,0,1]
	v_lshlrev_b32_e32 v0, 16, v6
	v_and_b32_e32 v1, 0xffff0000, v6
	v_pk_fma_f32 v[26:27], v[70:71], v[32:33], v[0:1] op_sel_hi:[1,0,1]
	v_lshlrev_b32_e32 v0, 16, v7
	v_and_b32_e32 v1, 0xffff0000, v7
	v_pk_fma_f32 v[6:7], v[72:73], v[32:33], v[0:1] op_sel_hi:[1,0,1]
	v_cvt_pk_bf16_f32 v0, v22, v23
	v_cvt_pk_bf16_f32 v1, v4, v5
	v_cvt_pk_bf16_f32 v2, v26, v27
	v_cvt_pk_bf16_f32 v3, v6, v7
	v_lshl_add_u64 v[28:29], v[20:21], 0, v[28:29]
	global_store_dwordx4 v[28:29], v[0:3], off sc0 sc1
	v_add_u32_e32 v33, s33, v33
	v_cndmask_b32_e32 v24, 0, v44, vcc
	v_mov_b32_e32 v25, v17
	v_cmp_lt_i32_e32 vcc, s25, v33
	s_or_b64 s[22:23], vcc, s[22:23]
	s_waitcnt vmcnt(3)
	v_lshlrev_b32_e32 v0, 16, v8
	v_and_b32_e32 v1, 0xffff0000, v8
	v_pk_fma_f32 v[22:23], v[22:23], v[36:37], v[0:1] op_sel_hi:[1,0,1]
	v_lshlrev_b32_e32 v0, 16, v9
	v_and_b32_e32 v1, 0xffff0000, v9
	v_pk_fma_f32 v[4:5], v[4:5], v[36:37], v[0:1] op_sel_hi:[1,0,1]
	v_lshlrev_b32_e32 v0, 16, v10
	v_and_b32_e32 v1, 0xffff0000, v10
	v_pk_fma_f32 v[8:9], v[26:27], v[36:37], v[0:1] op_sel_hi:[1,0,1]
	v_lshlrev_b32_e32 v0, 16, v11
	v_and_b32_e32 v1, 0xffff0000, v11
	v_pk_fma_f32 v[6:7], v[6:7], v[36:37], v[0:1] op_sel_hi:[1,0,1]
	v_cvt_pk_bf16_f32 v0, v22, v23
	v_cvt_pk_bf16_f32 v1, v4, v5
	v_cvt_pk_bf16_f32 v2, v8, v9
	v_cvt_pk_bf16_f32 v3, v6, v7
	v_lshl_add_u64 v[10:11], v[20:21], 0, v[34:35]
	global_store_dwordx4 v[10:11], v[0:3], off sc0 sc1
	v_add_u32_e32 v37, s24, v37
	s_nop 0
	v_lshlrev_b32_e32 v0, 16, v12
	v_and_b32_e32 v1, 0xffff0000, v12
	v_pk_fma_f32 v[10:11], v[22:23], v[40:41], v[0:1] op_sel_hi:[1,0,1]
	v_lshlrev_b32_e32 v0, 16, v13
	v_and_b32_e32 v1, 0xffff0000, v13
	v_pk_fma_f32 v[4:5], v[4:5], v[40:41], v[0:1] op_sel_hi:[1,0,1]
	v_lshlrev_b32_e32 v0, 16, v14
	v_and_b32_e32 v1, 0xffff0000, v14
	v_pk_fma_f32 v[8:9], v[8:9], v[40:41], v[0:1] op_sel_hi:[1,0,1]
	v_lshlrev_b32_e32 v0, 16, v15
	v_and_b32_e32 v1, 0xffff0000, v15
	v_pk_fma_f32 v[6:7], v[6:7], v[40:41], v[0:1] op_sel_hi:[1,0,1]
	v_cvt_pk_bf16_f32 v0, v10, v11
	v_cvt_pk_bf16_f32 v1, v4, v5
	v_cvt_pk_bf16_f32 v2, v8, v9
	v_cvt_pk_bf16_f32 v3, v6, v7
	v_lshl_add_u64 v[12:13], v[20:21], 0, v[38:39]
	global_store_dwordx4 v[12:13], v[0:3], off sc0 sc1
	v_lshl_add_u64 v[12:13], v[20:21], 0, v[64:65]
	s_nop 0
	v_lshlrev_b32_e32 v0, 16, v50
	v_and_b32_e32 v1, 0xffff0000, v50
	v_pk_fma_f32 v[10:11], v[10:11], v[62:63], v[0:1] op_sel_hi:[1,0,1]
	v_lshlrev_b32_e32 v0, 16, v51
	v_and_b32_e32 v1, 0xffff0000, v51
	v_pk_fma_f32 v[4:5], v[4:5], v[62:63], v[0:1] op_sel_hi:[1,0,1]
	v_lshlrev_b32_e32 v0, 16, v52
	v_and_b32_e32 v1, 0xffff0000, v52
	v_pk_fma_f32 v[8:9], v[8:9], v[62:63], v[0:1] op_sel_hi:[1,0,1]
	v_lshlrev_b32_e32 v0, 16, v53
	v_and_b32_e32 v1, 0xffff0000, v53
	v_pk_fma_f32 v[6:7], v[6:7], v[62:63], v[0:1] op_sel_hi:[1,0,1]
	v_cvt_pk_bf16_f32 v0, v10, v11
	v_cvt_pk_bf16_f32 v1, v4, v5
	v_cvt_pk_bf16_f32 v2, v8, v9
	v_cvt_pk_bf16_f32 v3, v6, v7
	global_store_dwordx4 v[12:13], v[0:3], off sc0 sc1
	v_lshl_add_u64 v[12:13], v[20:21], 0, v[68:69]
	s_waitcnt vmcnt(5)
	v_lshlrev_b32_e32 v0, 16, v54
	v_and_b32_e32 v1, 0xffff0000, v54
	v_pk_fma_f32 v[10:11], v[10:11], v[66:67], v[0:1] op_sel_hi:[1,0,1]
	v_lshlrev_b32_e32 v0, 16, v55
	v_and_b32_e32 v1, 0xffff0000, v55
	v_pk_fma_f32 v[4:5], v[4:5], v[66:67], v[0:1] op_sel_hi:[1,0,1]
	v_lshlrev_b32_e32 v0, 16, v56
	v_and_b32_e32 v1, 0xffff0000, v56
	v_pk_fma_f32 v[8:9], v[8:9], v[66:67], v[0:1] op_sel_hi:[1,0,1]
	v_lshlrev_b32_e32 v0, 16, v57
	v_and_b32_e32 v1, 0xffff0000, v57
	v_pk_fma_f32 v[6:7], v[6:7], v[66:67], v[0:1] op_sel_hi:[1,0,1]
	v_cvt_pk_bf16_f32 v0, v10, v11
	v_cvt_pk_bf16_f32 v1, v4, v5
	v_cvt_pk_bf16_f32 v2, v8, v9
	v_cvt_pk_bf16_f32 v3, v6, v7
	global_store_dwordx4 v[12:13], v[0:3], off sc0 sc1
	s_waitcnt vmcnt(5)
	s_nop 0
	v_lshlrev_b32_e32 v2, 16, v59
	v_and_b32_e32 v3, 0xffff0000, v59
	v_pk_fma_f32 v[2:3], v[4:5], v[18:19], v[2:3] op_sel_hi:[1,0,1]
	v_lshlrev_b32_e32 v4, 16, v60
	v_and_b32_e32 v5, 0xffff0000, v60
	v_lshlrev_b32_e32 v0, 16, v58
	v_and_b32_e32 v1, 0xffff0000, v58
	v_pk_fma_f32 v[4:5], v[8:9], v[18:19], v[4:5] op_sel_hi:[1,0,1]
	v_lshlrev_b32_e32 v8, 16, v61
	v_and_b32_e32 v9, 0xffff0000, v61
	v_pk_fma_f32 v[0:1], v[10:11], v[18:19], v[0:1] op_sel_hi:[1,0,1]
	v_pk_fma_f32 v[6:7], v[6:7], v[18:19], v[8:9] op_sel_hi:[1,0,1]
	v_cvt_pk_bf16_f32 v0, v0, v1
	v_cvt_pk_bf16_f32 v1, v2, v3
	v_cvt_pk_bf16_f32 v2, v4, v5
	v_cvt_pk_bf16_f32 v3, v6, v7
	v_lshl_add_u64 v[4:5], v[20:21], 0, v[24:25]
	global_store_dwordx4 v[4:5], v[0:3], off sc0 sc1
	s_andn2_b64 exec, exec, s[22:23]
	s_cbranch_execnz .LBB0_556
.LBB0_557:
	s_or_b64 exec, exec, s[20:21]
	s_waitcnt vmcnt(0)
	s_add_u32 s20, s92, 0xff43700
	v_readlane_b32 s0, v241, 0
	s_addc_u32 s21, s93, 0
	v_readlane_b32 s1, v241, 1
	s_barrier
	s_and_saveexec_b64 s[22:23], s[0:1]
	v_readlane_b32 s54, v240, 26
	v_readlane_b32 s55, v240, 27
	s_cbranch_execz .LBB0_560
	s_mov_b64 s[24:25], exec
	v_mbcnt_lo_u32_b32 v0, s24, 0
	s_waitcnt vmcnt(0)
	s_waitcnt vmcnt(0)
	v_mbcnt_hi_u32_b32 v0, s25, v0
	v_cmp_eq_u32_e32 vcc, 0, v0
	s_and_b64 s[26:27], exec, vcc
	s_mov_b64 exec, s[26:27]
	s_cbranch_execz .LBB0_560
	s_bcnt1_i32_b64 s24, s[24:25]
	v_mov_b32_e32 v0, 0
	v_mov_b32_e32 v1, s24
	global_atomic_add v0, v1, s[20:21]

; __device__ __forceinline__ unsigned xb_ld(unsigned* p)              { return __hip_atomic_load(p, __ATOMIC_RELAXED, __HIP_MEMORY_SCOPE_AGENT); }
; __device__ __forceinline__ unsigned xb_add(unsigned* p, unsigned v) { return __hip_atomic_fetch_add(p, v, __ATOMIC_RELAXED, __HIP_MEMORY_SCOPE_AGENT); }
; #define XB_SPIN(cond, bar) do { unsigned _sp = 0; while (cond) { __builtin_amdgcn_s_sleep(1); \
;     if ((++_sp & 255u) == 0u) { if (xb_ld(&(bar)[XB_TMO])) break; if (_sp > XB_SPIN_CAP) { atomicAdd(&(bar)[XB_TMO], 1u); break; } } } } while (0)
; __device__ __forceinline__ void xcd_barrier(const XcdBarrier& b) {
;     ...
;         const unsigned old = xb_add(&bar[XB_XSUB(b.x)], 1u);
;         const unsigned gen = old / nloc;
;         if (old + 1u == (gen + 1u) * nloc) {
;             __builtin_amdgcn_fence(__ATOMIC_RELEASE, "agent");
;             asm volatile("s_waitcnt vmcnt(0)" ::: "memory");
;             const unsigned og = xb_add(&bar[XB_TOP], 1u);
;             const unsigned tg = og / nx;
;             if (og + 1u == (tg + 1u) * nx) xb_add(&bar[XB_TOPGEN], 1u);
;             else XB_SPIN(xb_ld(&bar[XB_TOPGEN]) == tg, bar);
;             __builtin_amdgcn_fence(__ATOMIC_ACQUIRE, "agent");
;             xb_add(&bar[XB_XGEN(b.x)], 1u);
;             asm volatile("s_waitcnt vmcnt(0)" ::: "memory");
;         } else {
;             XB_SPIN(xb_ld(&bar[XB_XGEN(b.x)]) == gen, bar);
.LBB0_670:
	s_or_b64 exec, exec, s[18:19]
	v_cvt_f32_u32_e32 v4, v2
	s_waitcnt vmcnt(0)
	v_readfirstlane_b32 s18, v3
	v_sub_u32_e32 v3, 0, v2
	v_rcp_iflag_f32_e32 v4, v4
	v_add_u32_e32 v5, s18, v1
	v_mul_f32_e32 v4, 0x4f7ffffe, v4
	v_cvt_u32_f32_e32 v4, v4
	v_mul_lo_u32 v1, v3, v4
	v_mul_hi_u32 v1, v4, v1
	v_add_u32_e32 v1, v4, v1
	v_mul_hi_u32 v1, v5, v1
	v_mul_lo_u32 v3, v1, v2
	v_sub_u32_e32 v3, v5, v3
	v_add_u32_e32 v4, 1, v1
	v_cmp_ge_u32_e32 vcc, v3, v2
	s_nop 1
	v_cndmask_b32_e32 v1, v1, v4, vcc
	v_sub_u32_e32 v4, v3, v2
	v_cndmask_b32_e32 v3, v3, v4, vcc
	v_add_u32_e32 v4, 1, v1
	v_cmp_ge_u32_e32 vcc, v3, v2
	v_add_u32_e32 v3, 1, v5
	s_nop 0
	v_cndmask_b32_e32 v1, v1, v4, vcc
	v_mul_lo_u32 v4, v2, v1
	v_add_u32_e32 v2, v4, v2
	v_cmp_ne_u32_e32 vcc, v3, v2
	s_and_saveexec_b64 s[18:19], vcc
	s_xor_b64 s[18:19], exec, s[18:19]
	s_cbranch_execz .LBB0_684
	v_readlane_b32 s4, v240, 14
	s_waitcnt lgkmcnt(0)
	v_mov_b32_e32 v0, 0
	v_readlane_b32 s5, v240, 15
	s_nop 4
	buffer_inv sc1
	global_load_dword v2, v0, s[4:5] sc1
	s_waitcnt vmcnt(0)
	v_cmp_eq_u32_e32 vcc, v2, v1
	s_and_saveexec_b64 s[20:21], vcc
	s_cbranch_execz .LBB0_683
	s_mov_b32 s26, 1
	s_mov_b64 s[22:23], 0
	s_branch .LBB0_674

; __device__ __forceinline__ unsigned xb_ld(unsigned* p)              { return __hip_atomic_load(p, __ATOMIC_RELAXED, __HIP_MEMORY_SCOPE_AGENT); }
; #define XB_SPIN(cond, bar) do { unsigned _sp = 0; while (cond) { __builtin_amdgcn_s_sleep(1); \
;     if ((++_sp & 255u) == 0u) { if (xb_ld(&(bar)[XB_TMO])) break; if (_sp > XB_SPIN_CAP) { atomicAdd(&(bar)[XB_TMO], 1u); break; } } } } while (0)
; __device__ __forceinline__ void xcd_barrier(const XcdBarrier& b) {
;     ...
;             XB_SPIN(xb_ld(&bar[XB_XGEN(b.x)]) == gen, bar);
;             __builtin_amdgcn_fence(__ATOMIC_ACQUIRE, "agent");
;             asm volatile("s_waitcnt vmcnt(0)" ::: "memory");
.LBB0_683:
	s_or_b64 exec, exec, s[20:21]
	s_waitcnt vmcnt(0)
	s_waitcnt vmcnt(0)

; __device__ __forceinline__ unsigned xb_ld(unsigned* p)              { return __hip_atomic_load(p, __ATOMIC_RELAXED, __HIP_MEMORY_SCOPE_AGENT); }
; __device__ __forceinline__ unsigned xb_add(unsigned* p, unsigned v) { return __hip_atomic_fetch_add(p, v, __ATOMIC_RELAXED, __HIP_MEMORY_SCOPE_AGENT); }
; #define XB_SPIN(cond, bar) do { unsigned _sp = 0; while (cond) { __builtin_amdgcn_s_sleep(1); \
;     if ((++_sp & 255u) == 0u) { if (xb_ld(&(bar)[XB_TMO])) break; if (_sp > XB_SPIN_CAP) { atomicAdd(&(bar)[XB_TMO], 1u); break; } } } } while (0)
; __device__ __forceinline__ void xcd_barrier(const XcdBarrier& b) {
;     ...
;         const unsigned old = xb_add(&bar[XB_XSUB(b.x)], 1u);
;         const unsigned gen = old / nloc;
;         if (old + 1u == (gen + 1u) * nloc) {
;             __builtin_amdgcn_fence(__ATOMIC_RELEASE, "agent");
;             asm volatile("s_waitcnt vmcnt(0)" ::: "memory");
;             const unsigned og = xb_add(&bar[XB_TOP], 1u);
;             const unsigned tg = og / nx;
;             if (og + 1u == (tg + 1u) * nx) xb_add(&bar[XB_TOPGEN], 1u);
;             else XB_SPIN(xb_ld(&bar[XB_TOPGEN]) == tg, bar);
;             __builtin_amdgcn_fence(__ATOMIC_ACQUIRE, "agent");
;             xb_add(&bar[XB_XGEN(b.x)], 1u);
;             asm volatile("s_waitcnt vmcnt(0)" ::: "memory");
;         } else {
;             XB_SPIN(xb_ld(&bar[XB_XGEN(b.x)]) == gen, bar);
.LBB0_783:
	s_or_b64 exec, exec, s[8:9]
	v_cvt_f32_u32_e32 v4, v2
	s_waitcnt vmcnt(0)
	v_readfirstlane_b32 s8, v3
	v_sub_u32_e32 v3, 0, v2
	v_rcp_iflag_f32_e32 v4, v4
	v_add_u32_e32 v5, s8, v1
	v_mul_f32_e32 v4, 0x4f7ffffe, v4
	v_cvt_u32_f32_e32 v4, v4
	v_mul_lo_u32 v1, v3, v4
	v_mul_hi_u32 v1, v4, v1
	v_add_u32_e32 v1, v4, v1
	v_mul_hi_u32 v1, v5, v1
	v_mul_lo_u32 v3, v1, v2
	v_sub_u32_e32 v3, v5, v3
	v_add_u32_e32 v4, 1, v1
	v_cmp_ge_u32_e32 vcc, v3, v2
	s_nop 1
	v_cndmask_b32_e32 v1, v1, v4, vcc
	v_sub_u32_e32 v4, v3, v2
	v_cndmask_b32_e32 v3, v3, v4, vcc
	v_add_u32_e32 v4, 1, v1
	v_cmp_ge_u32_e32 vcc, v3, v2
	v_add_u32_e32 v3, 1, v5
	s_nop 0
	v_cndmask_b32_e32 v1, v1, v4, vcc
	v_mul_lo_u32 v4, v2, v1
	v_add_u32_e32 v2, v4, v2
	v_cmp_ne_u32_e32 vcc, v3, v2
	s_and_saveexec_b64 s[8:9], vcc
	s_xor_b64 s[8:9], exec, s[8:9]
	s_cbranch_execz .LBB0_797
	v_readlane_b32 s4, v240, 14
	s_waitcnt lgkmcnt(0)
	v_mov_b32_e32 v0, 0
	v_readlane_b32 s5, v240, 15
	s_nop 4
	buffer_inv sc1
	global_load_dword v2, v0, s[4:5] sc1
	s_waitcnt vmcnt(0)
	v_cmp_eq_u32_e32 vcc, v2, v1
	s_and_saveexec_b64 s[16:17], vcc
	s_cbranch_execz .LBB0_796
	s_mov_b32 s26, 1
	s_mov_b64 s[18:19], 0
	s_branch .LBB0_787

; __device__ __forceinline__ unsigned xb_ld(unsigned* p)              { return __hip_atomic_load(p, __ATOMIC_RELAXED, __HIP_MEMORY_SCOPE_AGENT); }
; #define XB_SPIN(cond, bar) do { unsigned _sp = 0; while (cond) { __builtin_amdgcn_s_sleep(1); \
;     if ((++_sp & 255u) == 0u) { if (xb_ld(&(bar)[XB_TMO])) break; if (_sp > XB_SPIN_CAP) { atomicAdd(&(bar)[XB_TMO], 1u); break; } } } } while (0)
; __device__ __forceinline__ void xcd_barrier(const XcdBarrier& b) {
;     ...
;             XB_SPIN(xb_ld(&bar[XB_XGEN(b.x)]) == gen, bar);
;             __builtin_amdgcn_fence(__ATOMIC_ACQUIRE, "agent");
;             asm volatile("s_waitcnt vmcnt(0)" ::: "memory");
.LBB0_796:
	s_or_b64 exec, exec, s[16:17]
	s_waitcnt vmcnt(0)
	s_waitcnt vmcnt(0)

; __device__ __forceinline__ unsigned xb_ld(unsigned* p)              { return __hip_atomic_load(p, __ATOMIC_RELAXED, __HIP_MEMORY_SCOPE_AGENT); }
; __device__ __forceinline__ unsigned xb_add(unsigned* p, unsigned v) { return __hip_atomic_fetch_add(p, v, __ATOMIC_RELAXED, __HIP_MEMORY_SCOPE_AGENT); }
; #define XB_SPIN(cond, bar) do { unsigned _sp = 0; while (cond) { __builtin_amdgcn_s_sleep(1); \
;     if ((++_sp & 255u) == 0u) { if (xb_ld(&(bar)[XB_TMO])) break; if (_sp > XB_SPIN_CAP) { atomicAdd(&(bar)[XB_TMO], 1u); break; } } } } while (0)
; __device__ __forceinline__ void xcd_barrier(const XcdBarrier& b) {
;     ...
;         const unsigned old = xb_add(&bar[XB_XSUB(b.x)], 1u);
;         const unsigned gen = old / nloc;
;         if (old + 1u == (gen + 1u) * nloc) {
;             __builtin_amdgcn_fence(__ATOMIC_RELEASE, "agent");
;             asm volatile("s_waitcnt vmcnt(0)" ::: "memory");
;             const unsigned og = xb_add(&bar[XB_TOP], 1u);
;             const unsigned tg = og / nx;
;             if (og + 1u == (tg + 1u) * nx) xb_add(&bar[XB_TOPGEN], 1u);
;             else XB_SPIN(xb_ld(&bar[XB_TOPGEN]) == tg, bar);
;             __builtin_amdgcn_fence(__ATOMIC_ACQUIRE, "agent");
;             xb_add(&bar[XB_XGEN(b.x)], 1u);
;             asm volatile("s_waitcnt vmcnt(0)" ::: "memory");
;         } else {
;             XB_SPIN(xb_ld(&bar[XB_XGEN(b.x)]) == gen, bar);
.LBB0_862:
	s_or_b64 exec, exec, s[4:5]
	v_cvt_f32_u32_e32 v4, v2
	s_waitcnt vmcnt(0)
	v_readfirstlane_b32 s4, v3
	v_sub_u32_e32 v3, 0, v2
	v_rcp_iflag_f32_e32 v4, v4
	v_add_u32_e32 v5, s4, v1
	v_mul_f32_e32 v4, 0x4f7ffffe, v4
	v_cvt_u32_f32_e32 v4, v4
	v_mul_lo_u32 v1, v3, v4
	v_mul_hi_u32 v1, v4, v1
	v_add_u32_e32 v1, v4, v1
	v_mul_hi_u32 v1, v5, v1
	v_mul_lo_u32 v3, v1, v2
	v_sub_u32_e32 v3, v5, v3
	v_add_u32_e32 v4, 1, v1
	v_cmp_ge_u32_e32 vcc, v3, v2
	s_nop 1
	v_cndmask_b32_e32 v1, v1, v4, vcc
	v_sub_u32_e32 v4, v3, v2
	v_cndmask_b32_e32 v3, v3, v4, vcc
	v_add_u32_e32 v4, 1, v1
	v_cmp_ge_u32_e32 vcc, v3, v2
	v_add_u32_e32 v3, 1, v5
	s_nop 0
	v_cndmask_b32_e32 v1, v1, v4, vcc
	v_mul_lo_u32 v4, v2, v1
	v_add_u32_e32 v2, v4, v2
	v_cmp_ne_u32_e32 vcc, v3, v2
	s_and_saveexec_b64 s[4:5], vcc
	s_xor_b64 s[4:5], exec, s[4:5]
	s_cbranch_execz .LBB0_876
	v_readlane_b32 s6, v240, 14
	s_waitcnt lgkmcnt(0)
	v_mov_b32_e32 v0, 0
	v_readlane_b32 s7, v240, 15
	s_nop 4
	buffer_inv sc1
	global_load_dword v2, v0, s[6:7] sc1
	s_waitcnt vmcnt(0)
	v_cmp_eq_u32_e32 vcc, v2, v1
	s_and_saveexec_b64 s[6:7], vcc
	s_cbranch_execz .LBB0_875
	s_mov_b32 s20, 1
	s_mov_b64 s[8:9], 0
	s_branch .LBB0_866

; __device__ __forceinline__ unsigned xb_ld(unsigned* p)              { return __hip_atomic_load(p, __ATOMIC_RELAXED, __HIP_MEMORY_SCOPE_AGENT); }
; #define XB_SPIN(cond, bar) do { unsigned _sp = 0; while (cond) { __builtin_amdgcn_s_sleep(1); \
;     if ((++_sp & 255u) == 0u) { if (xb_ld(&(bar)[XB_TMO])) break; if (_sp > XB_SPIN_CAP) { atomicAdd(&(bar)[XB_TMO], 1u); break; } } } } while (0)
; __device__ __forceinline__ void xcd_barrier(const XcdBarrier& b) {
;     ...
;             XB_SPIN(xb_ld(&bar[XB_XGEN(b.x)]) == gen, bar);
;             __builtin_amdgcn_fence(__ATOMIC_ACQUIRE, "agent");
;             asm volatile("s_waitcnt vmcnt(0)" ::: "memory");
.LBB0_875:
	s_or_b64 exec, exec, s[6:7]
	s_waitcnt vmcnt(0)
	s_waitcnt vmcnt(0)
